# P0 adaLN GEMV loop software-pipelined (two 16-row register banks, next batch in flight during the reduce)
# baseline (speedup 1.0000x reference)
.LBB0_22:
	s_mul_hi_i32 s4, s19, 0x66666667
	s_lshr_b32 s5, s4, 31
	s_ashr_i32 s22, s4, 4
	s_add_i32 s22, s22, s5
	s_mul_i32 s4, s22, 0x28
	s_lshl_b32 s6, s22, 7
	v_readlane_b32 s36, v241, 5
	s_sub_i32 s4, s19, s4
	s_ashr_i32 s7, s6, 31
	s_mul_i32 s5, s22, 0x900000
	v_readlane_b32 s40, v241, 9
	s_mul_hi_i32 s8, s6, 0x12000
	v_readlane_b32 s41, v241, 10
	s_add_u32 s9, s40, s5
	s_addc_u32 s23, s41, s8
	s_lshl_b32 s4, s4, 8
	s_ashr_i32 s5, s4, 31
	s_lshl_b64 s[4:5], s[4:5], 2
	s_add_u32 s8, s9, s4
	s_addc_u32 s9, s23, s5
	s_lshl_b64 s[6:7], s[6:7], 2
	s_add_u32 s6, s10, s6
	v_lshl_add_u64 v[8:9], s[8:9], 0, v[6:7]
	s_addc_u32 s7, s11, s7
	s_mov_b64 s[8:9], 0
	v_mov_b32_e32 v2, 0
	v_mov_b32_e32 v3, v7
	v_mov_b32_e32 v4, 0
	v_mov_b32_e32 v5, v7
	v_readlane_b32 s37, v241, 6
	v_readlane_b32 s38, v241, 7
	v_readlane_b32 s39, v241, 8
	v_readlane_b32 s42, v241, 11
	v_readlane_b32 s43, v241, 12
	v_readlane_b32 s44, v241, 13
	v_readlane_b32 s45, v241, 14
	v_readlane_b32 s46, v241, 15
	v_readlane_b32 s47, v241, 16
	v_readlane_b32 s48, v241, 17
	v_readlane_b32 s49, v241, 18
	v_readlane_b32 s50, v241, 19
	v_readlane_b32 s51, v241, 20
	v_mov_b32_e32 v106, v8
	v_mov_b32_e32 v107, v9
	s_mov_b32 s100, 0x12000
	s_mov_b32 s101, 0
	s_mov_b32 s8, 3
	global_load_dwordx4 v[10:13], v7, s[6:7] offset:-28
	global_load_dwordx4 v[14:17], v7, s[6:7] offset:-12
	global_load_dwordx4 v[18:21], v7, s[6:7] offset:4
	global_load_dwordx4 v[22:25], v7, s[6:7] offset:20
	global_load_dwordx4 v[26:29], v[106:107], off nt
	v_lshl_add_u64 v[106:107], v[106:107], 0, s[100:101]
	global_load_dwordx4 v[30:33], v[106:107], off nt
	v_lshl_add_u64 v[106:107], v[106:107], 0, s[100:101]
	global_load_dwordx4 v[34:37], v[106:107], off nt
	v_lshl_add_u64 v[106:107], v[106:107], 0, s[100:101]
	global_load_dwordx4 v[38:41], v[106:107], off nt
	v_lshl_add_u64 v[106:107], v[106:107], 0, s[100:101]
	global_load_dwordx4 v[42:45], v[106:107], off nt
	v_lshl_add_u64 v[106:107], v[106:107], 0, s[100:101]
	global_load_dwordx4 v[46:49], v[106:107], off nt
	v_lshl_add_u64 v[106:107], v[106:107], 0, s[100:101]
	global_load_dwordx4 v[50:53], v[106:107], off nt
	v_lshl_add_u64 v[106:107], v[106:107], 0, s[100:101]
	global_load_dwordx4 v[54:57], v[106:107], off nt
	v_lshl_add_u64 v[106:107], v[106:107], 0, s[100:101]
	global_load_dwordx4 v[58:61], v[106:107], off nt
	v_lshl_add_u64 v[106:107], v[106:107], 0, s[100:101]
	global_load_dwordx4 v[62:65], v[106:107], off nt
	v_lshl_add_u64 v[106:107], v[106:107], 0, s[100:101]
	global_load_dwordx4 v[66:69], v[106:107], off nt
	v_lshl_add_u64 v[106:107], v[106:107], 0, s[100:101]
	global_load_dwordx4 v[70:73], v[106:107], off nt
	v_lshl_add_u64 v[106:107], v[106:107], 0, s[100:101]
	global_load_dwordx4 v[74:77], v[106:107], off nt
	v_lshl_add_u64 v[106:107], v[106:107], 0, s[100:101]
	global_load_dwordx4 v[78:81], v[106:107], off nt
	v_lshl_add_u64 v[106:107], v[106:107], 0, s[100:101]
	global_load_dwordx4 v[82:85], v[106:107], off nt
	v_lshl_add_u64 v[106:107], v[106:107], 0, s[100:101]
	global_load_dwordx4 v[86:89], v[106:107], off nt
	v_lshl_add_u64 v[106:107], v[106:107], 0, s[100:101]
	s_add_u32 s6, s6, 64
	s_addc_u32 s7, s7, 0
.LBB0_23:
	global_load_dwordx4 v[108:111], v7, s[6:7] offset:-28
	global_load_dwordx4 v[112:115], v7, s[6:7] offset:-12
	global_load_dwordx4 v[116:119], v7, s[6:7] offset:4
	global_load_dwordx4 v[120:123], v7, s[6:7] offset:20
	global_load_dwordx4 v[148:151], v[106:107], off nt
	v_lshl_add_u64 v[106:107], v[106:107], 0, s[100:101]
	global_load_dwordx4 v[152:155], v[106:107], off nt
	v_lshl_add_u64 v[106:107], v[106:107], 0, s[100:101]
	global_load_dwordx4 v[156:159], v[106:107], off nt
	v_lshl_add_u64 v[106:107], v[106:107], 0, s[100:101]
	global_load_dwordx4 v[160:163], v[106:107], off nt
	v_lshl_add_u64 v[106:107], v[106:107], 0, s[100:101]
	global_load_dwordx4 v[164:167], v[106:107], off nt
	v_lshl_add_u64 v[106:107], v[106:107], 0, s[100:101]
	global_load_dwordx4 v[168:171], v[106:107], off nt
	v_lshl_add_u64 v[106:107], v[106:107], 0, s[100:101]
	global_load_dwordx4 v[172:175], v[106:107], off nt
	v_lshl_add_u64 v[106:107], v[106:107], 0, s[100:101]
	global_load_dwordx4 v[176:179], v[106:107], off nt
	v_lshl_add_u64 v[106:107], v[106:107], 0, s[100:101]
	global_load_dwordx4 v[180:183], v[106:107], off nt
	v_lshl_add_u64 v[106:107], v[106:107], 0, s[100:101]
	global_load_dwordx4 v[184:187], v[106:107], off nt
	v_lshl_add_u64 v[106:107], v[106:107], 0, s[100:101]
	global_load_dwordx4 v[188:191], v[106:107], off nt
	v_lshl_add_u64 v[106:107], v[106:107], 0, s[100:101]
	global_load_dwordx4 v[192:195], v[106:107], off nt
	v_lshl_add_u64 v[106:107], v[106:107], 0, s[100:101]
	global_load_dwordx4 v[196:199], v[106:107], off nt
	v_lshl_add_u64 v[106:107], v[106:107], 0, s[100:101]
	global_load_dwordx4 v[200:203], v[106:107], off nt
	v_lshl_add_u64 v[106:107], v[106:107], 0, s[100:101]
	global_load_dwordx4 v[204:207], v[106:107], off nt
	v_lshl_add_u64 v[106:107], v[106:107], 0, s[100:101]
	global_load_dwordx4 v[208:211], v[106:107], off nt
	v_lshl_add_u64 v[106:107], v[106:107], 0, s[100:101]
	s_add_u32 s6, s6, 64
	s_addc_u32 s7, s7, 0
	s_waitcnt vmcnt(36)
	v_mul_f32_e32 v90, 0xbfb8aa3b, v10
	v_mul_f32_e32 v91, 0xbfb8aa3b, v11
	v_mul_f32_e32 v92, 0xbfb8aa3b, v12
	v_mul_f32_e32 v93, 0xbfb8aa3b, v13
	v_mul_f32_e32 v94, 0xbfb8aa3b, v14
	v_mul_f32_e32 v95, 0xbfb8aa3b, v15
	v_mul_f32_e32 v96, 0xbfb8aa3b, v16
	v_mul_f32_e32 v97, 0xbfb8aa3b, v17
	v_mul_f32_e32 v98, 0xbfb8aa3b, v18
	v_mul_f32_e32 v99, 0xbfb8aa3b, v19
	v_mul_f32_e32 v100, 0xbfb8aa3b, v20
	v_mul_f32_e32 v101, 0xbfb8aa3b, v21
	v_mul_f32_e32 v102, 0xbfb8aa3b, v22
	v_mul_f32_e32 v103, 0xbfb8aa3b, v23
	v_mul_f32_e32 v104, 0xbfb8aa3b, v24
	v_mul_f32_e32 v105, 0xbfb8aa3b, v25
	v_exp_f32_e32 v90, v90
	v_exp_f32_e32 v91, v91
	v_exp_f32_e32 v92, v92
	v_exp_f32_e32 v93, v93
	v_exp_f32_e32 v94, v94
	v_exp_f32_e32 v95, v95
	v_exp_f32_e32 v96, v96
	v_exp_f32_e32 v97, v97
	v_exp_f32_e32 v98, v98
	v_exp_f32_e32 v99, v99
	v_exp_f32_e32 v100, v100
	v_exp_f32_e32 v101, v101
	v_exp_f32_e32 v102, v102
	v_exp_f32_e32 v103, v103
	v_exp_f32_e32 v104, v104
	v_exp_f32_e32 v105, v105
	v_add_f32_e32 v90, 1.0, v90
	v_add_f32_e32 v91, 1.0, v91
	v_add_f32_e32 v92, 1.0, v92
	v_add_f32_e32 v93, 1.0, v93
	v_add_f32_e32 v94, 1.0, v94
	v_add_f32_e32 v95, 1.0, v95
	v_add_f32_e32 v96, 1.0, v96
	v_add_f32_e32 v97, 1.0, v97
	v_add_f32_e32 v98, 1.0, v98
	v_add_f32_e32 v99, 1.0, v99
	v_add_f32_e32 v100, 1.0, v100
	v_add_f32_e32 v101, 1.0, v101
	v_add_f32_e32 v102, 1.0, v102
	v_add_f32_e32 v103, 1.0, v103
	v_add_f32_e32 v104, 1.0, v104
	v_add_f32_e32 v105, 1.0, v105
	v_rcp_f32_e32 v90, v90
	v_rcp_f32_e32 v91, v91
	v_rcp_f32_e32 v92, v92
	v_rcp_f32_e32 v93, v93
	v_rcp_f32_e32 v94, v94
	v_rcp_f32_e32 v95, v95
	v_rcp_f32_e32 v96, v96
	v_rcp_f32_e32 v97, v97
	v_rcp_f32_e32 v98, v98
	v_rcp_f32_e32 v99, v99
	v_rcp_f32_e32 v100, v100
	v_rcp_f32_e32 v101, v101
	v_rcp_f32_e32 v102, v102
	v_rcp_f32_e32 v103, v103
	v_rcp_f32_e32 v104, v104
	v_rcp_f32_e32 v105, v105
	v_mul_f32_e32 v10, v10, v90
	v_mul_f32_e32 v11, v11, v91
	v_mul_f32_e32 v12, v12, v92
	v_mul_f32_e32 v13, v13, v93
	v_mul_f32_e32 v14, v14, v94
	v_mul_f32_e32 v15, v15, v95
	v_mul_f32_e32 v16, v16, v96
	v_mul_f32_e32 v17, v17, v97
	v_mul_f32_e32 v18, v18, v98
	v_mul_f32_e32 v19, v19, v99
	v_mul_f32_e32 v20, v20, v100
	v_mul_f32_e32 v21, v21, v101
	v_mul_f32_e32 v22, v22, v102
	v_mul_f32_e32 v23, v23, v103
	v_mul_f32_e32 v24, v24, v104
	v_mul_f32_e32 v25, v25, v105
	s_waitcnt vmcnt(35)
	v_pk_fma_f32 v[4:5], v[28:29], v[10:11], v[4:5] op_sel_hi:[1,0,1]
	v_pk_fma_f32 v[2:3], v[26:27], v[10:11], v[2:3] op_sel_hi:[1,0,1]
	s_waitcnt vmcnt(34)
	v_pk_fma_f32 v[4:5], v[32:33], v[10:11], v[4:5] op_sel:[0,1,0] op_sel_hi:[1,1,1]
	v_pk_fma_f32 v[2:3], v[30:31], v[10:11], v[2:3] op_sel:[0,1,0] op_sel_hi:[1,1,1]
	s_waitcnt vmcnt(33)
	v_pk_fma_f32 v[4:5], v[36:37], v[12:13], v[4:5] op_sel_hi:[1,0,1]
	v_pk_fma_f32 v[2:3], v[34:35], v[12:13], v[2:3] op_sel_hi:[1,0,1]
	s_waitcnt vmcnt(32)
	v_pk_fma_f32 v[4:5], v[40:41], v[12:13], v[4:5] op_sel:[0,1,0] op_sel_hi:[1,1,1]
	v_pk_fma_f32 v[2:3], v[38:39], v[12:13], v[2:3] op_sel:[0,1,0] op_sel_hi:[1,1,1]
	s_waitcnt vmcnt(31)
	v_pk_fma_f32 v[4:5], v[44:45], v[14:15], v[4:5] op_sel_hi:[1,0,1]
	v_pk_fma_f32 v[2:3], v[42:43], v[14:15], v[2:3] op_sel_hi:[1,0,1]
	s_waitcnt vmcnt(30)
	v_pk_fma_f32 v[4:5], v[48:49], v[14:15], v[4:5] op_sel:[0,1,0] op_sel_hi:[1,1,1]
	v_pk_fma_f32 v[2:3], v[46:47], v[14:15], v[2:3] op_sel:[0,1,0] op_sel_hi:[1,1,1]
	s_waitcnt vmcnt(29)
	v_pk_fma_f32 v[4:5], v[52:53], v[16:17], v[4:5] op_sel_hi:[1,0,1]
	v_pk_fma_f32 v[2:3], v[50:51], v[16:17], v[2:3] op_sel_hi:[1,0,1]
	s_waitcnt vmcnt(28)
	v_pk_fma_f32 v[4:5], v[56:57], v[16:17], v[4:5] op_sel:[0,1,0] op_sel_hi:[1,1,1]
	v_pk_fma_f32 v[2:3], v[54:55], v[16:17], v[2:3] op_sel:[0,1,0] op_sel_hi:[1,1,1]
	s_waitcnt vmcnt(27)
	v_pk_fma_f32 v[4:5], v[60:61], v[18:19], v[4:5] op_sel_hi:[1,0,1]
	v_pk_fma_f32 v[2:3], v[58:59], v[18:19], v[2:3] op_sel_hi:[1,0,1]
	s_waitcnt vmcnt(26)
	v_pk_fma_f32 v[4:5], v[64:65], v[18:19], v[4:5] op_sel:[0,1,0] op_sel_hi:[1,1,1]
	v_pk_fma_f32 v[2:3], v[62:63], v[18:19], v[2:3] op_sel:[0,1,0] op_sel_hi:[1,1,1]
	s_waitcnt vmcnt(25)
	v_pk_fma_f32 v[4:5], v[68:69], v[20:21], v[4:5] op_sel_hi:[1,0,1]
	v_pk_fma_f32 v[2:3], v[66:67], v[20:21], v[2:3] op_sel_hi:[1,0,1]
	s_waitcnt vmcnt(24)
	v_pk_fma_f32 v[4:5], v[72:73], v[20:21], v[4:5] op_sel:[0,1,0] op_sel_hi:[1,1,1]
	v_pk_fma_f32 v[2:3], v[70:71], v[20:21], v[2:3] op_sel:[0,1,0] op_sel_hi:[1,1,1]
	s_waitcnt vmcnt(23)
	v_pk_fma_f32 v[4:5], v[76:77], v[22:23], v[4:5] op_sel_hi:[1,0,1]
	v_pk_fma_f32 v[2:3], v[74:75], v[22:23], v[2:3] op_sel_hi:[1,0,1]
	s_waitcnt vmcnt(22)
	v_pk_fma_f32 v[4:5], v[80:81], v[22:23], v[4:5] op_sel:[0,1,0] op_sel_hi:[1,1,1]
	v_pk_fma_f32 v[2:3], v[78:79], v[22:23], v[2:3] op_sel:[0,1,0] op_sel_hi:[1,1,1]
	s_waitcnt vmcnt(21)
	v_pk_fma_f32 v[4:5], v[84:85], v[24:25], v[4:5] op_sel_hi:[1,0,1]
	v_pk_fma_f32 v[2:3], v[82:83], v[24:25], v[2:3] op_sel_hi:[1,0,1]
	s_waitcnt vmcnt(20)
	v_pk_fma_f32 v[4:5], v[88:89], v[24:25], v[4:5] op_sel:[0,1,0] op_sel_hi:[1,1,1]
	v_pk_fma_f32 v[2:3], v[86:87], v[24:25], v[2:3] op_sel:[0,1,0] op_sel_hi:[1,1,1]
	global_load_dwordx4 v[10:13], v7, s[6:7] offset:-28
	global_load_dwordx4 v[14:17], v7, s[6:7] offset:-12
	global_load_dwordx4 v[18:21], v7, s[6:7] offset:4
	global_load_dwordx4 v[22:25], v7, s[6:7] offset:20
	global_load_dwordx4 v[26:29], v[106:107], off nt
	v_lshl_add_u64 v[106:107], v[106:107], 0, s[100:101]
	global_load_dwordx4 v[30:33], v[106:107], off nt
	v_lshl_add_u64 v[106:107], v[106:107], 0, s[100:101]
	global_load_dwordx4 v[34:37], v[106:107], off nt
	v_lshl_add_u64 v[106:107], v[106:107], 0, s[100:101]
	global_load_dwordx4 v[38:41], v[106:107], off nt
	v_lshl_add_u64 v[106:107], v[106:107], 0, s[100:101]
	global_load_dwordx4 v[42:45], v[106:107], off nt
	v_lshl_add_u64 v[106:107], v[106:107], 0, s[100:101]
	global_load_dwordx4 v[46:49], v[106:107], off nt
	v_lshl_add_u64 v[106:107], v[106:107], 0, s[100:101]
	global_load_dwordx4 v[50:53], v[106:107], off nt
	v_lshl_add_u64 v[106:107], v[106:107], 0, s[100:101]
	global_load_dwordx4 v[54:57], v[106:107], off nt
	v_lshl_add_u64 v[106:107], v[106:107], 0, s[100:101]
	global_load_dwordx4 v[58:61], v[106:107], off nt
	v_lshl_add_u64 v[106:107], v[106:107], 0, s[100:101]
	global_load_dwordx4 v[62:65], v[106:107], off nt
	v_lshl_add_u64 v[106:107], v[106:107], 0, s[100:101]
	global_load_dwordx4 v[66:69], v[106:107], off nt
	v_lshl_add_u64 v[106:107], v[106:107], 0, s[100:101]
	global_load_dwordx4 v[70:73], v[106:107], off nt
	v_lshl_add_u64 v[106:107], v[106:107], 0, s[100:101]
	global_load_dwordx4 v[74:77], v[106:107], off nt
	v_lshl_add_u64 v[106:107], v[106:107], 0, s[100:101]
	global_load_dwordx4 v[78:81], v[106:107], off nt
	v_lshl_add_u64 v[106:107], v[106:107], 0, s[100:101]
	global_load_dwordx4 v[82:85], v[106:107], off nt
	v_lshl_add_u64 v[106:107], v[106:107], 0, s[100:101]
	global_load_dwordx4 v[86:89], v[106:107], off nt
	v_lshl_add_u64 v[106:107], v[106:107], 0, s[100:101]
	s_add_u32 s6, s6, 64
	s_addc_u32 s7, s7, 0
	s_waitcnt vmcnt(36)
	v_mul_f32_e32 v212, 0xbfb8aa3b, v108
	v_mul_f32_e32 v213, 0xbfb8aa3b, v109
	v_mul_f32_e32 v214, 0xbfb8aa3b, v110
	v_mul_f32_e32 v215, 0xbfb8aa3b, v111
	v_mul_f32_e32 v216, 0xbfb8aa3b, v112
	v_mul_f32_e32 v217, 0xbfb8aa3b, v113
	v_mul_f32_e32 v218, 0xbfb8aa3b, v114
	v_mul_f32_e32 v219, 0xbfb8aa3b, v115
	v_mul_f32_e32 v220, 0xbfb8aa3b, v116
	v_mul_f32_e32 v221, 0xbfb8aa3b, v117
	v_mul_f32_e32 v222, 0xbfb8aa3b, v118
	v_mul_f32_e32 v223, 0xbfb8aa3b, v119
	v_mul_f32_e32 v224, 0xbfb8aa3b, v120
	v_mul_f32_e32 v225, 0xbfb8aa3b, v121
	v_mul_f32_e32 v226, 0xbfb8aa3b, v122
	v_mul_f32_e32 v227, 0xbfb8aa3b, v123
	v_exp_f32_e32 v212, v212
	v_exp_f32_e32 v213, v213
	v_exp_f32_e32 v214, v214
	v_exp_f32_e32 v215, v215
	v_exp_f32_e32 v216, v216
	v_exp_f32_e32 v217, v217
	v_exp_f32_e32 v218, v218
	v_exp_f32_e32 v219, v219
	v_exp_f32_e32 v220, v220
	v_exp_f32_e32 v221, v221
	v_exp_f32_e32 v222, v222
	v_exp_f32_e32 v223, v223
	v_exp_f32_e32 v224, v224
	v_exp_f32_e32 v225, v225
	v_exp_f32_e32 v226, v226
	v_exp_f32_e32 v227, v227
	v_add_f32_e32 v212, 1.0, v212
	v_add_f32_e32 v213, 1.0, v213
	v_add_f32_e32 v214, 1.0, v214
	v_add_f32_e32 v215, 1.0, v215
	v_add_f32_e32 v216, 1.0, v216
	v_add_f32_e32 v217, 1.0, v217
	v_add_f32_e32 v218, 1.0, v218
	v_add_f32_e32 v219, 1.0, v219
	v_add_f32_e32 v220, 1.0, v220
	v_add_f32_e32 v221, 1.0, v221
	v_add_f32_e32 v222, 1.0, v222
	v_add_f32_e32 v223, 1.0, v223
	v_add_f32_e32 v224, 1.0, v224
	v_add_f32_e32 v225, 1.0, v225
	v_add_f32_e32 v226, 1.0, v226
	v_add_f32_e32 v227, 1.0, v227
	v_rcp_f32_e32 v212, v212
	v_rcp_f32_e32 v213, v213
	v_rcp_f32_e32 v214, v214
	v_rcp_f32_e32 v215, v215
	v_rcp_f32_e32 v216, v216
	v_rcp_f32_e32 v217, v217
	v_rcp_f32_e32 v218, v218
	v_rcp_f32_e32 v219, v219
	v_rcp_f32_e32 v220, v220
	v_rcp_f32_e32 v221, v221
	v_rcp_f32_e32 v222, v222
	v_rcp_f32_e32 v223, v223
	v_rcp_f32_e32 v224, v224
	v_rcp_f32_e32 v225, v225
	v_rcp_f32_e32 v226, v226
	v_rcp_f32_e32 v227, v227
	v_mul_f32_e32 v108, v108, v212
	v_mul_f32_e32 v109, v109, v213
	v_mul_f32_e32 v110, v110, v214
	v_mul_f32_e32 v111, v111, v215
	v_mul_f32_e32 v112, v112, v216
	v_mul_f32_e32 v113, v113, v217
	v_mul_f32_e32 v114, v114, v218
	v_mul_f32_e32 v115, v115, v219
	v_mul_f32_e32 v116, v116, v220
	v_mul_f32_e32 v117, v117, v221
	v_mul_f32_e32 v118, v118, v222
	v_mul_f32_e32 v119, v119, v223
	v_mul_f32_e32 v120, v120, v224
	v_mul_f32_e32 v121, v121, v225
	v_mul_f32_e32 v122, v122, v226
	v_mul_f32_e32 v123, v123, v227
	s_waitcnt vmcnt(35)
	v_pk_fma_f32 v[4:5], v[150:151], v[108:109], v[4:5] op_sel_hi:[1,0,1]
	v_pk_fma_f32 v[2:3], v[148:149], v[108:109], v[2:3] op_sel_hi:[1,0,1]
	s_waitcnt vmcnt(34)
	v_pk_fma_f32 v[4:5], v[154:155], v[108:109], v[4:5] op_sel:[0,1,0] op_sel_hi:[1,1,1]
	v_pk_fma_f32 v[2:3], v[152:153], v[108:109], v[2:3] op_sel:[0,1,0] op_sel_hi:[1,1,1]
	s_waitcnt vmcnt(33)
	v_pk_fma_f32 v[4:5], v[158:159], v[110:111], v[4:5] op_sel_hi:[1,0,1]
	v_pk_fma_f32 v[2:3], v[156:157], v[110:111], v[2:3] op_sel_hi:[1,0,1]
	s_waitcnt vmcnt(32)
	v_pk_fma_f32 v[4:5], v[162:163], v[110:111], v[4:5] op_sel:[0,1,0] op_sel_hi:[1,1,1]
	v_pk_fma_f32 v[2:3], v[160:161], v[110:111], v[2:3] op_sel:[0,1,0] op_sel_hi:[1,1,1]
	s_waitcnt vmcnt(31)
	v_pk_fma_f32 v[4:5], v[166:167], v[112:113], v[4:5] op_sel_hi:[1,0,1]
	v_pk_fma_f32 v[2:3], v[164:165], v[112:113], v[2:3] op_sel_hi:[1,0,1]
	s_waitcnt vmcnt(30)
	v_pk_fma_f32 v[4:5], v[170:171], v[112:113], v[4:5] op_sel:[0,1,0] op_sel_hi:[1,1,1]
	v_pk_fma_f32 v[2:3], v[168:169], v[112:113], v[2:3] op_sel:[0,1,0] op_sel_hi:[1,1,1]
	s_waitcnt vmcnt(29)
	v_pk_fma_f32 v[4:5], v[174:175], v[114:115], v[4:5] op_sel_hi:[1,0,1]
	v_pk_fma_f32 v[2:3], v[172:173], v[114:115], v[2:3] op_sel_hi:[1,0,1]
	s_waitcnt vmcnt(28)
	v_pk_fma_f32 v[4:5], v[178:179], v[114:115], v[4:5] op_sel:[0,1,0] op_sel_hi:[1,1,1]
	v_pk_fma_f32 v[2:3], v[176:177], v[114:115], v[2:3] op_sel:[0,1,0] op_sel_hi:[1,1,1]
	s_waitcnt vmcnt(27)
	v_pk_fma_f32 v[4:5], v[182:183], v[116:117], v[4:5] op_sel_hi:[1,0,1]
	v_pk_fma_f32 v[2:3], v[180:181], v[116:117], v[2:3] op_sel_hi:[1,0,1]
	s_waitcnt vmcnt(26)
	v_pk_fma_f32 v[4:5], v[186:187], v[116:117], v[4:5] op_sel:[0,1,0] op_sel_hi:[1,1,1]
	v_pk_fma_f32 v[2:3], v[184:185], v[116:117], v[2:3] op_sel:[0,1,0] op_sel_hi:[1,1,1]
	s_waitcnt vmcnt(25)
	v_pk_fma_f32 v[4:5], v[190:191], v[118:119], v[4:5] op_sel_hi:[1,0,1]
	v_pk_fma_f32 v[2:3], v[188:189], v[118:119], v[2:3] op_sel_hi:[1,0,1]
	s_waitcnt vmcnt(24)
	v_pk_fma_f32 v[4:5], v[194:195], v[118:119], v[4:5] op_sel:[0,1,0] op_sel_hi:[1,1,1]
	v_pk_fma_f32 v[2:3], v[192:193], v[118:119], v[2:3] op_sel:[0,1,0] op_sel_hi:[1,1,1]
	s_waitcnt vmcnt(23)
	v_pk_fma_f32 v[4:5], v[198:199], v[120:121], v[4:5] op_sel_hi:[1,0,1]
	v_pk_fma_f32 v[2:3], v[196:197], v[120:121], v[2:3] op_sel_hi:[1,0,1]
	s_waitcnt vmcnt(22)
	v_pk_fma_f32 v[4:5], v[202:203], v[120:121], v[4:5] op_sel:[0,1,0] op_sel_hi:[1,1,1]
	v_pk_fma_f32 v[2:3], v[200:201], v[120:121], v[2:3] op_sel:[0,1,0] op_sel_hi:[1,1,1]
	s_waitcnt vmcnt(21)
	v_pk_fma_f32 v[4:5], v[206:207], v[122:123], v[4:5] op_sel_hi:[1,0,1]
	v_pk_fma_f32 v[2:3], v[204:205], v[122:123], v[2:3] op_sel_hi:[1,0,1]
	s_waitcnt vmcnt(20)
	v_pk_fma_f32 v[4:5], v[210:211], v[122:123], v[4:5] op_sel:[0,1,0] op_sel_hi:[1,1,1]
	v_pk_fma_f32 v[2:3], v[208:209], v[122:123], v[2:3] op_sel:[0,1,0] op_sel_hi:[1,1,1]
	s_sub_u32 s8, s8, 1
	s_cmp_lg_u32 s8, 0
	s_cbranch_scc1 .LBB0_23
	global_load_dwordx4 v[108:111], v7, s[6:7] offset:-28
	global_load_dwordx4 v[112:115], v7, s[6:7] offset:-12
	global_load_dwordx4 v[116:119], v7, s[6:7] offset:4
	global_load_dwordx4 v[120:123], v7, s[6:7] offset:20
	global_load_dwordx4 v[148:151], v[106:107], off nt
	v_lshl_add_u64 v[106:107], v[106:107], 0, s[100:101]
	global_load_dwordx4 v[152:155], v[106:107], off nt
	v_lshl_add_u64 v[106:107], v[106:107], 0, s[100:101]
	global_load_dwordx4 v[156:159], v[106:107], off nt
	v_lshl_add_u64 v[106:107], v[106:107], 0, s[100:101]
	global_load_dwordx4 v[160:163], v[106:107], off nt
	v_lshl_add_u64 v[106:107], v[106:107], 0, s[100:101]
	global_load_dwordx4 v[164:167], v[106:107], off nt
	v_lshl_add_u64 v[106:107], v[106:107], 0, s[100:101]
	global_load_dwordx4 v[168:171], v[106:107], off nt
	v_lshl_add_u64 v[106:107], v[106:107], 0, s[100:101]
	global_load_dwordx4 v[172:175], v[106:107], off nt
	v_lshl_add_u64 v[106:107], v[106:107], 0, s[100:101]
	global_load_dwordx4 v[176:179], v[106:107], off nt
	v_lshl_add_u64 v[106:107], v[106:107], 0, s[100:101]
	global_load_dwordx4 v[180:183], v[106:107], off nt
	v_lshl_add_u64 v[106:107], v[106:107], 0, s[100:101]
	global_load_dwordx4 v[184:187], v[106:107], off nt
	v_lshl_add_u64 v[106:107], v[106:107], 0, s[100:101]
	global_load_dwordx4 v[188:191], v[106:107], off nt
	v_lshl_add_u64 v[106:107], v[106:107], 0, s[100:101]
	global_load_dwordx4 v[192:195], v[106:107], off nt
	v_lshl_add_u64 v[106:107], v[106:107], 0, s[100:101]
	global_load_dwordx4 v[196:199], v[106:107], off nt
	v_lshl_add_u64 v[106:107], v[106:107], 0, s[100:101]
	global_load_dwordx4 v[200:203], v[106:107], off nt
	v_lshl_add_u64 v[106:107], v[106:107], 0, s[100:101]
	global_load_dwordx4 v[204:207], v[106:107], off nt
	v_lshl_add_u64 v[106:107], v[106:107], 0, s[100:101]
	global_load_dwordx4 v[208:211], v[106:107], off nt
	v_lshl_add_u64 v[106:107], v[106:107], 0, s[100:101]
	s_add_u32 s6, s6, 64
	s_addc_u32 s7, s7, 0
	s_waitcnt vmcnt(36)
	v_mul_f32_e32 v90, 0xbfb8aa3b, v10
	v_mul_f32_e32 v91, 0xbfb8aa3b, v11
	v_mul_f32_e32 v92, 0xbfb8aa3b, v12
	v_mul_f32_e32 v93, 0xbfb8aa3b, v13
	v_mul_f32_e32 v94, 0xbfb8aa3b, v14
	v_mul_f32_e32 v95, 0xbfb8aa3b, v15
	v_mul_f32_e32 v96, 0xbfb8aa3b, v16
	v_mul_f32_e32 v97, 0xbfb8aa3b, v17
	v_mul_f32_e32 v98, 0xbfb8aa3b, v18
	v_mul_f32_e32 v99, 0xbfb8aa3b, v19
	v_mul_f32_e32 v100, 0xbfb8aa3b, v20
	v_mul_f32_e32 v101, 0xbfb8aa3b, v21
	v_mul_f32_e32 v102, 0xbfb8aa3b, v22
	v_mul_f32_e32 v103, 0xbfb8aa3b, v23
	v_mul_f32_e32 v104, 0xbfb8aa3b, v24
	v_mul_f32_e32 v105, 0xbfb8aa3b, v25
	v_exp_f32_e32 v90, v90
	v_exp_f32_e32 v91, v91
	v_exp_f32_e32 v92, v92
	v_exp_f32_e32 v93, v93
	v_exp_f32_e32 v94, v94
	v_exp_f32_e32 v95, v95
	v_exp_f32_e32 v96, v96
	v_exp_f32_e32 v97, v97
	v_exp_f32_e32 v98, v98
	v_exp_f32_e32 v99, v99
	v_exp_f32_e32 v100, v100
	v_exp_f32_e32 v101, v101
	v_exp_f32_e32 v102, v102
	v_exp_f32_e32 v103, v103
	v_exp_f32_e32 v104, v104
	v_exp_f32_e32 v105, v105
	v_add_f32_e32 v90, 1.0, v90
	v_add_f32_e32 v91, 1.0, v91
	v_add_f32_e32 v92, 1.0, v92
	v_add_f32_e32 v93, 1.0, v93
	v_add_f32_e32 v94, 1.0, v94
	v_add_f32_e32 v95, 1.0, v95
	v_add_f32_e32 v96, 1.0, v96
	v_add_f32_e32 v97, 1.0, v97
	v_add_f32_e32 v98, 1.0, v98
	v_add_f32_e32 v99, 1.0, v99
	v_add_f32_e32 v100, 1.0, v100
	v_add_f32_e32 v101, 1.0, v101
	v_add_f32_e32 v102, 1.0, v102
	v_add_f32_e32 v103, 1.0, v103
	v_add_f32_e32 v104, 1.0, v104
	v_add_f32_e32 v105, 1.0, v105
	v_rcp_f32_e32 v90, v90
	v_rcp_f32_e32 v91, v91
	v_rcp_f32_e32 v92, v92
	v_rcp_f32_e32 v93, v93
	v_rcp_f32_e32 v94, v94
	v_rcp_f32_e32 v95, v95
	v_rcp_f32_e32 v96, v96
	v_rcp_f32_e32 v97, v97
	v_rcp_f32_e32 v98, v98
	v_rcp_f32_e32 v99, v99
	v_rcp_f32_e32 v100, v100
	v_rcp_f32_e32 v101, v101
	v_rcp_f32_e32 v102, v102
	v_rcp_f32_e32 v103, v103
	v_rcp_f32_e32 v104, v104
	v_rcp_f32_e32 v105, v105
	v_mul_f32_e32 v10, v10, v90
	v_mul_f32_e32 v11, v11, v91
	v_mul_f32_e32 v12, v12, v92
	v_mul_f32_e32 v13, v13, v93
	v_mul_f32_e32 v14, v14, v94
	v_mul_f32_e32 v15, v15, v95
	v_mul_f32_e32 v16, v16, v96
	v_mul_f32_e32 v17, v17, v97
	v_mul_f32_e32 v18, v18, v98
	v_mul_f32_e32 v19, v19, v99
	v_mul_f32_e32 v20, v20, v100
	v_mul_f32_e32 v21, v21, v101
	v_mul_f32_e32 v22, v22, v102
	v_mul_f32_e32 v23, v23, v103
	v_mul_f32_e32 v24, v24, v104
	v_mul_f32_e32 v25, v25, v105
	s_waitcnt vmcnt(35)
	v_pk_fma_f32 v[4:5], v[28:29], v[10:11], v[4:5] op_sel_hi:[1,0,1]
	v_pk_fma_f32 v[2:3], v[26:27], v[10:11], v[2:3] op_sel_hi:[1,0,1]
	s_waitcnt vmcnt(34)
	v_pk_fma_f32 v[4:5], v[32:33], v[10:11], v[4:5] op_sel:[0,1,0] op_sel_hi:[1,1,1]
	v_pk_fma_f32 v[2:3], v[30:31], v[10:11], v[2:3] op_sel:[0,1,0] op_sel_hi:[1,1,1]
	s_waitcnt vmcnt(33)
	v_pk_fma_f32 v[4:5], v[36:37], v[12:13], v[4:5] op_sel_hi:[1,0,1]
	v_pk_fma_f32 v[2:3], v[34:35], v[12:13], v[2:3] op_sel_hi:[1,0,1]
	s_waitcnt vmcnt(32)
	v_pk_fma_f32 v[4:5], v[40:41], v[12:13], v[4:5] op_sel:[0,1,0] op_sel_hi:[1,1,1]
	v_pk_fma_f32 v[2:3], v[38:39], v[12:13], v[2:3] op_sel:[0,1,0] op_sel_hi:[1,1,1]
	s_waitcnt vmcnt(31)
	v_pk_fma_f32 v[4:5], v[44:45], v[14:15], v[4:5] op_sel_hi:[1,0,1]
	v_pk_fma_f32 v[2:3], v[42:43], v[14:15], v[2:3] op_sel_hi:[1,0,1]
	s_waitcnt vmcnt(30)
	v_pk_fma_f32 v[4:5], v[48:49], v[14:15], v[4:5] op_sel:[0,1,0] op_sel_hi:[1,1,1]
	v_pk_fma_f32 v[2:3], v[46:47], v[14:15], v[2:3] op_sel:[0,1,0] op_sel_hi:[1,1,1]
	s_waitcnt vmcnt(29)
	v_pk_fma_f32 v[4:5], v[52:53], v[16:17], v[4:5] op_sel_hi:[1,0,1]
	v_pk_fma_f32 v[2:3], v[50:51], v[16:17], v[2:3] op_sel_hi:[1,0,1]
	s_waitcnt vmcnt(28)
	v_pk_fma_f32 v[4:5], v[56:57], v[16:17], v[4:5] op_sel:[0,1,0] op_sel_hi:[1,1,1]
	v_pk_fma_f32 v[2:3], v[54:55], v[16:17], v[2:3] op_sel:[0,1,0] op_sel_hi:[1,1,1]
	s_waitcnt vmcnt(27)
	v_pk_fma_f32 v[4:5], v[60:61], v[18:19], v[4:5] op_sel_hi:[1,0,1]
	v_pk_fma_f32 v[2:3], v[58:59], v[18:19], v[2:3] op_sel_hi:[1,0,1]
	s_waitcnt vmcnt(26)
	v_pk_fma_f32 v[4:5], v[64:65], v[18:19], v[4:5] op_sel:[0,1,0] op_sel_hi:[1,1,1]
	v_pk_fma_f32 v[2:3], v[62:63], v[18:19], v[2:3] op_sel:[0,1,0] op_sel_hi:[1,1,1]
	s_waitcnt vmcnt(25)
	v_pk_fma_f32 v[4:5], v[68:69], v[20:21], v[4:5] op_sel_hi:[1,0,1]
	v_pk_fma_f32 v[2:3], v[66:67], v[20:21], v[2:3] op_sel_hi:[1,0,1]
	s_waitcnt vmcnt(24)
	v_pk_fma_f32 v[4:5], v[72:73], v[20:21], v[4:5] op_sel:[0,1,0] op_sel_hi:[1,1,1]
	v_pk_fma_f32 v[2:3], v[70:71], v[20:21], v[2:3] op_sel:[0,1,0] op_sel_hi:[1,1,1]
	s_waitcnt vmcnt(23)
	v_pk_fma_f32 v[4:5], v[76:77], v[22:23], v[4:5] op_sel_hi:[1,0,1]
	v_pk_fma_f32 v[2:3], v[74:75], v[22:23], v[2:3] op_sel_hi:[1,0,1]
	s_waitcnt vmcnt(22)
	v_pk_fma_f32 v[4:5], v[80:81], v[22:23], v[4:5] op_sel:[0,1,0] op_sel_hi:[1,1,1]
	v_pk_fma_f32 v[2:3], v[78:79], v[22:23], v[2:3] op_sel:[0,1,0] op_sel_hi:[1,1,1]
	s_waitcnt vmcnt(21)
	v_pk_fma_f32 v[4:5], v[84:85], v[24:25], v[4:5] op_sel_hi:[1,0,1]
	v_pk_fma_f32 v[2:3], v[82:83], v[24:25], v[2:3] op_sel_hi:[1,0,1]
	s_waitcnt vmcnt(20)
	v_pk_fma_f32 v[4:5], v[88:89], v[24:25], v[4:5] op_sel:[0,1,0] op_sel_hi:[1,1,1]
	v_pk_fma_f32 v[2:3], v[86:87], v[24:25], v[2:3] op_sel:[0,1,0] op_sel_hi:[1,1,1]
	s_waitcnt vmcnt(16)
	v_mul_f32_e32 v212, 0xbfb8aa3b, v108
	v_mul_f32_e32 v213, 0xbfb8aa3b, v109
	v_mul_f32_e32 v214, 0xbfb8aa3b, v110
	v_mul_f32_e32 v215, 0xbfb8aa3b, v111
	v_mul_f32_e32 v216, 0xbfb8aa3b, v112
	v_mul_f32_e32 v217, 0xbfb8aa3b, v113
	v_mul_f32_e32 v218, 0xbfb8aa3b, v114
	v_mul_f32_e32 v219, 0xbfb8aa3b, v115
	v_mul_f32_e32 v220, 0xbfb8aa3b, v116
	v_mul_f32_e32 v221, 0xbfb8aa3b, v117
	v_mul_f32_e32 v222, 0xbfb8aa3b, v118
	v_mul_f32_e32 v223, 0xbfb8aa3b, v119
	v_mul_f32_e32 v224, 0xbfb8aa3b, v120
	v_mul_f32_e32 v225, 0xbfb8aa3b, v121
	v_mul_f32_e32 v226, 0xbfb8aa3b, v122
	v_mul_f32_e32 v227, 0xbfb8aa3b, v123
	v_exp_f32_e32 v212, v212
	v_exp_f32_e32 v213, v213
	v_exp_f32_e32 v214, v214
	v_exp_f32_e32 v215, v215
	v_exp_f32_e32 v216, v216
	v_exp_f32_e32 v217, v217
	v_exp_f32_e32 v218, v218
	v_exp_f32_e32 v219, v219
	v_exp_f32_e32 v220, v220
	v_exp_f32_e32 v221, v221
	v_exp_f32_e32 v222, v222
	v_exp_f32_e32 v223, v223
	v_exp_f32_e32 v224, v224
	v_exp_f32_e32 v225, v225
	v_exp_f32_e32 v226, v226
	v_exp_f32_e32 v227, v227
	v_add_f32_e32 v212, 1.0, v212
	v_add_f32_e32 v213, 1.0, v213
	v_add_f32_e32 v214, 1.0, v214
	v_add_f32_e32 v215, 1.0, v215
	v_add_f32_e32 v216, 1.0, v216
	v_add_f32_e32 v217, 1.0, v217
	v_add_f32_e32 v218, 1.0, v218
	v_add_f32_e32 v219, 1.0, v219
	v_add_f32_e32 v220, 1.0, v220
	v_add_f32_e32 v221, 1.0, v221
	v_add_f32_e32 v222, 1.0, v222
	v_add_f32_e32 v223, 1.0, v223
	v_add_f32_e32 v224, 1.0, v224
	v_add_f32_e32 v225, 1.0, v225
	v_add_f32_e32 v226, 1.0, v226
	v_add_f32_e32 v227, 1.0, v227
	v_rcp_f32_e32 v212, v212
	v_rcp_f32_e32 v213, v213
	v_rcp_f32_e32 v214, v214
	v_rcp_f32_e32 v215, v215
	v_rcp_f32_e32 v216, v216
	v_rcp_f32_e32 v217, v217
	v_rcp_f32_e32 v218, v218
	v_rcp_f32_e32 v219, v219
	v_rcp_f32_e32 v220, v220
	v_rcp_f32_e32 v221, v221
	v_rcp_f32_e32 v222, v222
	v_rcp_f32_e32 v223, v223
	v_rcp_f32_e32 v224, v224
	v_rcp_f32_e32 v225, v225
	v_rcp_f32_e32 v226, v226
	v_rcp_f32_e32 v227, v227
	v_mul_f32_e32 v108, v108, v212
	v_mul_f32_e32 v109, v109, v213
	v_mul_f32_e32 v110, v110, v214
	v_mul_f32_e32 v111, v111, v215
	v_mul_f32_e32 v112, v112, v216
	v_mul_f32_e32 v113, v113, v217
	v_mul_f32_e32 v114, v114, v218
	v_mul_f32_e32 v115, v115, v219
	v_mul_f32_e32 v116, v116, v220
	v_mul_f32_e32 v117, v117, v221
	v_mul_f32_e32 v118, v118, v222
	v_mul_f32_e32 v119, v119, v223
	v_mul_f32_e32 v120, v120, v224
	v_mul_f32_e32 v121, v121, v225
	v_mul_f32_e32 v122, v122, v226
	v_mul_f32_e32 v123, v123, v227
	s_waitcnt vmcnt(15)
	v_pk_fma_f32 v[4:5], v[150:151], v[108:109], v[4:5] op_sel_hi:[1,0,1]
	v_pk_fma_f32 v[2:3], v[148:149], v[108:109], v[2:3] op_sel_hi:[1,0,1]
	s_waitcnt vmcnt(14)
	v_pk_fma_f32 v[4:5], v[154:155], v[108:109], v[4:5] op_sel:[0,1,0] op_sel_hi:[1,1,1]
	v_pk_fma_f32 v[2:3], v[152:153], v[108:109], v[2:3] op_sel:[0,1,0] op_sel_hi:[1,1,1]
	s_waitcnt vmcnt(13)
	v_pk_fma_f32 v[4:5], v[158:159], v[110:111], v[4:5] op_sel_hi:[1,0,1]
	v_pk_fma_f32 v[2:3], v[156:157], v[110:111], v[2:3] op_sel_hi:[1,0,1]
	s_waitcnt vmcnt(12)
	v_pk_fma_f32 v[4:5], v[162:163], v[110:111], v[4:5] op_sel:[0,1,0] op_sel_hi:[1,1,1]
	v_pk_fma_f32 v[2:3], v[160:161], v[110:111], v[2:3] op_sel:[0,1,0] op_sel_hi:[1,1,1]
	s_waitcnt vmcnt(11)
	v_pk_fma_f32 v[4:5], v[166:167], v[112:113], v[4:5] op_sel_hi:[1,0,1]
	v_pk_fma_f32 v[2:3], v[164:165], v[112:113], v[2:3] op_sel_hi:[1,0,1]
	s_waitcnt vmcnt(10)
	v_pk_fma_f32 v[4:5], v[170:171], v[112:113], v[4:5] op_sel:[0,1,0] op_sel_hi:[1,1,1]
	v_pk_fma_f32 v[2:3], v[168:169], v[112:113], v[2:3] op_sel:[0,1,0] op_sel_hi:[1,1,1]
	s_waitcnt vmcnt(9)
	v_pk_fma_f32 v[4:5], v[174:175], v[114:115], v[4:5] op_sel_hi:[1,0,1]
	v_pk_fma_f32 v[2:3], v[172:173], v[114:115], v[2:3] op_sel_hi:[1,0,1]
	s_waitcnt vmcnt(8)
	v_pk_fma_f32 v[4:5], v[178:179], v[114:115], v[4:5] op_sel:[0,1,0] op_sel_hi:[1,1,1]
	v_pk_fma_f32 v[2:3], v[176:177], v[114:115], v[2:3] op_sel:[0,1,0] op_sel_hi:[1,1,1]
	s_waitcnt vmcnt(7)
	v_pk_fma_f32 v[4:5], v[182:183], v[116:117], v[4:5] op_sel_hi:[1,0,1]
	v_pk_fma_f32 v[2:3], v[180:181], v[116:117], v[2:3] op_sel_hi:[1,0,1]
	s_waitcnt vmcnt(6)
	v_pk_fma_f32 v[4:5], v[186:187], v[116:117], v[4:5] op_sel:[0,1,0] op_sel_hi:[1,1,1]
	v_pk_fma_f32 v[2:3], v[184:185], v[116:117], v[2:3] op_sel:[0,1,0] op_sel_hi:[1,1,1]
	s_waitcnt vmcnt(5)
	v_pk_fma_f32 v[4:5], v[190:191], v[118:119], v[4:5] op_sel_hi:[1,0,1]
	v_pk_fma_f32 v[2:3], v[188:189], v[118:119], v[2:3] op_sel_hi:[1,0,1]
	s_waitcnt vmcnt(4)
	v_pk_fma_f32 v[4:5], v[194:195], v[118:119], v[4:5] op_sel:[0,1,0] op_sel_hi:[1,1,1]
	v_pk_fma_f32 v[2:3], v[192:193], v[118:119], v[2:3] op_sel:[0,1,0] op_sel_hi:[1,1,1]
	s_waitcnt vmcnt(3)
	v_pk_fma_f32 v[4:5], v[198:199], v[120:121], v[4:5] op_sel_hi:[1,0,1]
	v_pk_fma_f32 v[2:3], v[196:197], v[120:121], v[2:3] op_sel_hi:[1,0,1]
	s_waitcnt vmcnt(2)
	v_pk_fma_f32 v[4:5], v[202:203], v[120:121], v[4:5] op_sel:[0,1,0] op_sel_hi:[1,1,1]
	v_pk_fma_f32 v[2:3], v[200:201], v[120:121], v[2:3] op_sel:[0,1,0] op_sel_hi:[1,1,1]
	s_waitcnt vmcnt(1)
	v_pk_fma_f32 v[4:5], v[206:207], v[122:123], v[4:5] op_sel_hi:[1,0,1]
	v_pk_fma_f32 v[2:3], v[204:205], v[122:123], v[2:3] op_sel_hi:[1,0,1]
	s_waitcnt vmcnt(0)
	v_pk_fma_f32 v[4:5], v[210:211], v[122:123], v[4:5] op_sel:[0,1,0] op_sel_hi:[1,1,1]
	v_pk_fma_f32 v[2:3], v[208:209], v[122:123], v[2:3] op_sel:[0,1,0] op_sel_hi:[1,1,1]
	s_mul_hi_i32 s6, s22, 0x12000
	s_mul_i32 s22, s22, 0x12000
	s_add_u32 s7, s0, s22
	s_addc_u32 s6, s1, s6
	s_add_u32 s4, s7, s4
	s_addc_u32 s5, s6, s5
	s_add_i32 s19, s19, s86
	s_cmpk_gt_i32 s19, 0x27f
	global_store_dwordx4 v6, v[2:5], s[4:5]
	s_cbranch_scc0 .LBB0_22
